# three of next tile's first QK0 fragment reads hoisted above the trailing PV1 MFMAs; QK0 k-step order permuted
# baseline (speedup 1.0000x reference)
; __device__ __forceinline__ int v_rd_base(int lane) { return ((lane & 3) << 3) | (((lane >> 2) & 3) << 6) | (((lane >> 4) & 1) << 5) | (((lane >> 5) & 1) << 8); }
; #define DMA_K(k0, s) do { DMA_KN(k0, s); DMA_KR(k0, s); } while (0)
; #define DMA_V(k0, off) do { const char* vb_ = (const char*)Vh + (size_t)(k0) * (LDV * 2); \
;     GLDS(vb_ + v_off[0], V_lds + (off) + (wid * 2) * 1024); GLDS(vb_ + v_off[1], V_lds + (off) + (wid * 2 + 1) * 1024); } while (0)
; __device__ __forceinline__ void attn_unit(const bf16_t* __restrict__ Qb, const bf16_t* __restrict__ KNh, const bf16_t* __restrict__ KRs, const bf16_t* __restrict__ Vh,
;                                           bf16_t* __restrict__ Ob, float* __restrict__ ssa, int seq, char* lds) {
;   const int tid = threadIdx.x, wid = __builtin_amdgcn_readfirstlane(tid >> 6), lane = tid & 63, r32 = lane & 31, hi = lane >> 5;
;   char* V_lds = lds + OFF_V; char* KN_lds = lds + OFF_KN; char* KR_lds = lds + OFF_KR;
;   float* ws = (float*)(lds + OFF_WS) + wid * 64; float* li_l = ws; float* al_l = ws + 32;
;   float m_reg = -1e30f, l_reg = 0; f32x16 o[4] = {}; bf16x8 qr[12];
;   const bf16_t* Qw = Qb + (long)(wid * QBLK + r32) * LDQ + hi * 8;
; #pragma unroll
;   for (int d0 = 0; d0 < 12; ++d0) qr[d0] = *reinterpret_cast<const bf16x8*>(Qw + d0 * 16);
;   const int vb0 = (int)(uintptr_t)V_lds + v_rd_base(lane);
;   unsigned kn_off[2], v_off[2], kr_off;
; #pragma unroll
;   for (int i = 0; i < 2; ++i) {
;     const int q = (wid * 2 + i) * 64 + lane;
;     { const int row = q >> 4, c = (q & 15) ^ (row & 15); kn_off[i] = (unsigned)(row * LDKN * 2 + c * 16); }
;     { const int sub = q >> 5, kk = (sub >> 2) * 8 + ((q & 31) >> 2), cc = (sub & 3) * 32 + (q & 3) * 8, k = (kk & ~0xC) | ((kk & 4) << 1) | ((kk & 8) >> 1);
;       v_off[i] = (unsigned)(k * LDV * 2 + cc * 2); }
;   }
;   { const int q = wid * 64 + lane, row = q >> 3, c = (q & 7) ^ ((row >> 1) & 7); kr_off = (unsigned)(row * LDKR * 2 + c * 16); }
;   typedef __attribute__((address_space(3))) unsigned lds_u32;
;     ...
;   f32x16 p0, p1; float al0, al1; bf16x8 pa0, pa1, pa2, pa3; const int NT = seq / KVBLK;
;     ...
;   DMA_K(0, 0); DMA_V(0, 0);
;   asm volatile("s_waitcnt vmcnt(0)" ::: "memory"); __syncthreads();
.LBB0_516:
	s_ashr_i32 s59, s58, 31
	s_mul_i32 s61, s58, 0x900
	s_mul_hi_i32 s60, s58, 0x900
	s_add_u32 s63, s13, s61
	s_addc_u32 s65, s14, s60
	s_mul_i32 s60, s16, 0xc0
	s_ashr_i32 s61, s60, 31
	s_lshl_b64 s[60:61], s[60:61], 1
	s_add_u32 s64, s63, s60
	s_addc_u32 s65, s65, s61
	s_ashr_i32 s63, s62, 31
	s_mul_i32 s92, s62, 0x600
	s_mul_hi_i32 s90, s62, 0x600
	s_add_u32 s66, s15, s92
	s_addc_u32 s67, s22, s90
	s_lshl_b32 s60, s16, 7
	s_ashr_i32 s61, s60, 31
	s_lshl_b64 s[60:61], s[60:61], 1
	s_add_u32 s66, s66, s60
	s_addc_u32 s67, s67, s61
	s_add_u32 s18, s66, 0x18000
	s_addc_u32 s19, s67, 0
	s_lshl_b64 s[62:63], s[62:63], 7
	s_add_u32 s86, s23, s62
	s_addc_u32 s87, s28, s63
	s_add_u32 s20, s86, 0x2000
	s_addc_u32 s21, s87, 0
	s_add_u32 s16, s29, s92
	s_addc_u32 s80, s30, s90
	s_add_u32 s88, s16, s60
	v_readfirstlane_b32 s16, v146
	s_addc_u32 s89, s80, s61
	s_add_u32 s34, s88, 0x18000
	s_addc_u32 s35, s89, 0
	s_lshr_b32 s80, s16, 6
	s_and_b32 s93, s16, 0xffffffc0
	s_lshl_b32 s16, s80, 5
	v_or_b32_e32 v0, s16, v148
	v_mov_b64_e32 v[2:3], s[64:65]
	v_mad_u64_u32 v[2:3], s[64:65], v0, s75, v[2:3]
	v_lshl_add_u64 v[2:3], v[2:3], 0, v[150:151]
	s_lshl_b32 s64, s80, 7
	global_load_dwordx4 v[98:101], v[2:3], off
	global_load_dwordx4 v[102:105], v[2:3], off offset:32
	global_load_dwordx4 v[106:109], v[2:3], off offset:64
	global_load_dwordx4 v[110:113], v[2:3], off offset:96
	global_load_dwordx4 v[114:117], v[2:3], off offset:128
	global_load_dwordx4 v[118:121], v[2:3], off offset:160
	global_load_dwordx4 v[122:125], v[2:3], off offset:192
	global_load_dwordx4 v[126:129], v[2:3], off offset:224
	global_load_dwordx4 v[130:133], v[2:3], off offset:256
	global_load_dwordx4 v[134:137], v[2:3], off offset:288
	global_load_dwordx4 v[138:141], v[2:3], off offset:320
	global_load_dwordx4 v[142:145], v[2:3], off offset:352
	v_or_b32_e32 v2, s64, v147
	s_ashr_i32 s64, s64, 4
	s_and_b32 s94, s64, -16
	s_lshr_b32 s64, s64, 1
	s_and_b32 s95, s64, 4
	v_or_b32_e32 v0, s94, v173
	v_or_b32_e32 v0, s95, v0
	v_mul_lo_u32 v3, v0, s74
	v_ashrrev_i32_e32 v0, 4, v2
	v_xor_b32_e32 v4, v0, v146
	v_or_b32_e32 v5, 64, v2
	s_movk_i32 s64, 0x60
	v_mul_lo_u32 v0, v0, s74
	v_lshlrev_b32_e32 v4, 4, v4
	v_ashrrev_i32_e32 v2, 4, v5
	v_and_or_b32 v5, v5, s64, v172
	v_and_or_b32 v0, v4, s73, v0
	v_or_b32_e32 v4, v3, v174
	v_lshl_or_b32 v3, v5, 1, v3
	v_or_b32_e32 v5, s93, v147
	s_movk_i32 s64, 0x70
	v_bitop3_b32 v7, v5, s64, v149 bitop3:0x48
	s_lshl_b32 s64, s80, 11
	s_add_i32 s81, s64, 0
	v_xor_b32_e32 v6, v2, v146
	s_add_i32 s82, s81, 0x8000
	v_mul_lo_u32 v2, v2, s74
	v_lshlrev_b32_e32 v6, 4, v6
	s_mov_b32 m0, s82
	s_add_i32 s83, s81, 0x8400
	v_and_or_b32 v2, v6, s73, v2
	global_load_lds_dwordx4 v0, s[66:67]
	s_mov_b32 m0, s83
	v_lshlrev_b32_e32 v6, 4, v5
	global_load_lds_dwordx4 v2, s[66:67]
	s_lshl_b32 s66, s80, 10
	s_add_i32 s84, s66, 0
	s_add_i32 s85, s84, 0x10000
	v_and_or_b32 v5, v6, s76, v7
	s_mov_b32 m0, s85
	s_lshl_b32 s64, s93, 2
	global_load_lds_dwordx4 v5, s[86:87]
	s_mov_b32 m0, s81
	s_add_i32 s86, s81, 0x400
	global_load_lds_dwordx4 v4, s[88:89]
	s_mov_b32 m0, s86
	s_add_i32 s80, s64, 0
	global_load_lds_dwordx4 v3, s[88:89]
	v_mov_b32_e32 v152, v0
	v_mov_b32_e32 v153, v2
	v_mov_b32_e32 v154, v5
	v_mov_b32_e32 v155, v4
	v_mov_b32_e32 v156, v3
	v_add_u32_e32 v157, 0x10000, v177
	v_add_u32_e32 v158, 0x10000, v178
	v_add_u32_e32 v159, 0x10000, v179
	v_add_u32_e32 v160, 0x10000, v180
	s_add_i32 s80, s80, 0x14000
	s_add_u32 s64, s92, s60
	s_addc_u32 s65, s90, s61
	s_or_b32 s67, s95, s94
	v_add_u32_e32 v4, s67, v173
	v_mul_lo_u32 v6, v4, s74
	v_or_b32_e32 v4, v184, v6
	v_mov_b32_e32 v5, v1
	v_or3_b32 v4, v183, v6, v186
	v_or_b32_e32 v4, s66, v185
	v_mov_b32_e32 v3, v1
	v_and_or_b32 v4, v4, s76, v7
	v_mov_b32_e32 v14, v1
	v_mov_b32_e32 v15, v1
	s_waitcnt vmcnt(0)
	v_mov_b32_e32 v0, v1
	v_mov_b32_e32 v2, v1
	v_mov_b32_e32 v4, v1
	v_mov_b32_e32 v6, v1
	v_mov_b32_e32 v7, v1
	v_mov_b32_e32 v8, v1
	v_mov_b32_e32 v9, v1
	v_mov_b32_e32 v10, v1
	v_mov_b32_e32 v11, v1
	v_mov_b32_e32 v12, v1
	v_mov_b32_e32 v13, v1
	v_mov_b64_e32 v[64:65], v[14:15]
	v_mov_b64_e32 v[48:49], v[14:15]
	v_mov_b64_e32 v[32:33], v[14:15]
	v_mov_b64_e32 v[62:63], v[12:13]
	v_mov_b64_e32 v[60:61], v[10:11]
	v_mov_b64_e32 v[58:59], v[8:9]
	v_mov_b64_e32 v[56:57], v[6:7]
	v_mov_b64_e32 v[54:55], v[4:5]
	v_mov_b64_e32 v[52:53], v[2:3]
	v_mov_b64_e32 v[50:51], v[0:1]
	v_mov_b64_e32 v[46:47], v[12:13]
	v_mov_b64_e32 v[44:45], v[10:11]
	v_mov_b64_e32 v[42:43], v[8:9]
	v_mov_b64_e32 v[40:41], v[6:7]
	v_mov_b64_e32 v[38:39], v[4:5]
	v_mov_b64_e32 v[36:37], v[2:3]
	v_mov_b64_e32 v[34:35], v[0:1]
	v_mov_b64_e32 v[30:31], v[12:13]
	v_mov_b64_e32 v[28:29], v[10:11]
	v_mov_b64_e32 v[26:27], v[8:9]
	v_mov_b64_e32 v[24:25], v[6:7]
	v_mov_b64_e32 v[22:23], v[4:5]
	v_mov_b64_e32 v[20:21], v[2:3]
	v_mov_b64_e32 v[18:19], v[0:1]
	v_mov_b64_e32 v[16:17], v[14:15]
	s_mov_b32 s87, 2
	v_lshl_add_u32 v196, v148, 2, s80
	v_mov_b32_e32 v161, 0xf149f2ca
	s_mov_b32 s99, 0xff800000
	v_mov_b32_e32 v250, 0
	v_mov_b32_e32 v251, 0
	v_mov_b32_e32 v253, 0x3f80
	v_mov_b32_e32 v254, 0
	v_mov_b32_e32 v255, 0
	v_mbcnt_lo_u32_b32 v252, -1, 0
	v_mbcnt_hi_u32_b32 v252, -1, v252
	v_cmp_gt_u32_e32 vcc, 32, v252
	s_nop 1
	v_cndmask_b32_e32 v252, 0, v253, vcc
	v_mov_b32_e32 v253, 0
	v_mov_b32_e32 v197, 0
	v_mov_b64_e32 v[14:15], v[12:13]
	v_mov_b64_e32 v[12:13], v[10:11]
	v_mov_b64_e32 v[10:11], v[8:9]
	v_mov_b64_e32 v[8:9], v[6:7]
	v_mov_b64_e32 v[6:7], v[4:5]
	v_mov_b64_e32 v[4:5], v[2:3]
	v_mov_b64_e32 v[2:3], v[0:1]
	s_waitcnt vmcnt(0) lgkmcnt(0)
	s_barrier
	ds_read_b128 v[66:69], v187 offset:32768
	ds_read_b128 v[74:77], v189 offset:32768
	ds_read_b128 v[78:81], v190 offset:32768
	s_branch .LBB0_519

; #define VWAIT(N, f) asm volatile("s_waitcnt lgkmcnt(" #N ")" : "+v"(f.l0), "+v"(f.h0), "+v"(f.l1), "+v"(f.h1) :: "memory")
; template <int H, int D0> __device__ __forceinline__ VFrag pv_rd(int vb) {
;   VFrag f; f.l0 = tr_read<v_rd_off(D0, 2 * H, 0)>(vb); f.h0 = tr_read<v_rd_off(D0, 2 * H, 1)>(vb); f.l1 = tr_read<v_rd_off(D0, 2 * H + 1, 0)>(vb); f.h1 = tr_read<v_rd_off(D0, 2 * H + 1, 1)>(vb); return f;
; }
; __device__ __forceinline__ void pv_mma(f32x16& od, VFrag& f, bf16x8 paL, bf16x8 paH) {
;     ...
;   od = __builtin_amdgcn_mfma_f32_32x32x16_bf16(paL, PK(f.l0, f.h0), od, 0, 0, 0);
;   od = __builtin_amdgcn_mfma_f32_32x32x16_bf16(paH, PK(f.l1, f.h1), od, 0, 0, 0);
;     ...
; }
; template <int H> __device__ __forceinline__ void pv_half(f32x16* o, int vb, bf16x8 paL, bf16x8 paH) {
;   VFrag fa = pv_rd<H, 0>(vb), fb = pv_rd<H, 1>(vb);
;   VWAIT(4, fa); pv_mma(o[0], fa, paL, paH);
;   fa = pv_rd<H, 2>(vb);
;   VWAIT(4, fb); pv_mma(o[1], fb, paL, paH);
;   fb = pv_rd<H, 3>(vb);
;   VWAIT(4, fa); pv_mma(o[2], fa, paL, paH);
;   VWAIT(0, fb); pv_mma(o[3], fb, paL, paH);
; }
.LBB0_518:
	v_fma_f32 v202, v197, v0, v198
	v_fma_f32 v0, v202, v200, v201
	v_fma_f32 v202, v0, v249, v91
	ds_read_b64_tr_b16 v[204:205], v181 offset:0x2000
	ds_read_b64_tr_b16 v[206:207], v181 offset:0x2800
	ds_read_b64_tr_b16 v[82:83], v181 offset:0x2200
	ds_read_b64_tr_b16 v[84:85], v181 offset:0x2a00
	ds_read_b64_tr_b16 v[212:213], v181 offset:0x2400
	ds_read_b64_tr_b16 v[214:215], v181 offset:0x2c00
	ds_read_b64_tr_b16 v[216:217], v181 offset:0x2600
	ds_read_b64_tr_b16 v[218:219], v181 offset:0x2e00
	ds_read_b64_tr_b16 v[208:209], v181 offset:0x3000
	ds_read_b64_tr_b16 v[210:211], v181 offset:0x3800
	ds_read_b64_tr_b16 v[86:87], v181 offset:0x3200
	ds_read_b64_tr_b16 v[88:89], v181 offset:0x3a00
	v_exp_f32_e32 v74, v74
	v_exp_f32_e32 v75, v75
	s_add_i32 s87, s87, 2
	s_and_b64 vcc, exec, s[62:63]
	s_waitcnt lgkmcnt(10)
	v_mfma_f32_32x32x16_bf16 v[50:65], v[66:69], v[204:207], v[50:65]
	ds_read_b64_tr_b16 v[204:205], v181 offset:0x3400
	ds_read_b64_tr_b16 v[206:207], v181 offset:0x3c00
	v_exp_f32_e32 v76, v76
	v_exp_f32_e32 v77, v77
	v_add_f32_e32 v163, v74, v163
	v_add_f32_e32 v163, v75, v163
	s_waitcnt lgkmcnt(10)
	v_mfma_f32_32x32x16_bf16 v[34:49], v[66:69], v[82:85], v[34:49]
	ds_read_b64_tr_b16 v[82:83], v181 offset:0x3600
	ds_read_b64_tr_b16 v[84:85], v181 offset:0x3e00
	v_exp_f32_e32 v78, v78
	v_exp_f32_e32 v79, v79
	v_add_f32_e32 v163, v76, v163
	v_add_f32_e32 v163, v77, v163
	v_cvt_pk_bf16_f32 v70, v74, v75
	v_cvt_pk_bf16_f32 v71, v76, v77
	s_waitcnt lgkmcnt(10)
	v_mfma_f32_32x32x16_bf16 v[18:33], v[66:69], v[212:215], v[18:33]
	v_exp_f32_e32 v80, v80
	v_exp_f32_e32 v81, v81
	v_add_f32_e32 v163, v78, v163
	v_add_f32_e32 v163, v79, v163
	s_waitcnt lgkmcnt(8)
	v_mfma_f32_32x32x16_bf16 v[2:17], v[66:69], v[216:219], v[2:17]
	v_cvt_pk_bf16_f32 v72, v78, v79
	v_add_f32_e32 v163, v80, v163
	v_add_f32_e32 v163, v81, v163
	v_cvt_pk_bf16_f32 v73, v80, v81
	s_nop 1
	v_permlane32_swap_b32_e32 v70, v72
	v_permlane32_swap_b32_e32 v71, v73
	s_nop 1
	s_waitcnt vmcnt(0) lgkmcnt(0)
	v_mfma_f32_32x32x16_bf16 v[50:65], v[70:73], v[208:211], v[50:65]
	s_barrier
	ds_read_b128 v[66:69], v187 offset:32768
	ds_read_b128 v[74:77], v189 offset:32768
	ds_read_b128 v[78:81], v190 offset:32768
	v_mfma_f32_32x32x16_bf16 v[34:49], v[70:73], v[86:89], v[34:49]
	v_mfma_f32_32x32x16_bf16 v[18:33], v[70:73], v[204:207], v[18:33]
	v_mfma_f32_32x32x16_bf16 v[2:17], v[70:73], v[82:85], v[2:17]
	v_fma_f32 v197, v202, v93, v163
	s_cbranch_vccnz .LBB0_542

; template <int H> __device__ __forceinline__ void qkt_half(f32x16& p, const char* Kn, const char* Kr, const bf16x8* qr, int r32, int hi) {
;   p = f32x16{};
; #pragma unroll
;   for (int d0 = 0; d0 < 8; ++d0) { const int cb = (d0 * 16 + hi * 8) * 2;
;     const bf16x8 f = *reinterpret_cast<const bf16x8*>(Kn + KSWZ(32 * H + r32, cb)); p = __builtin_amdgcn_mfma_f32_32x32x16_bf16(f, qr[d0], p, 0, 0, 0); }
; #pragma unroll
;   for (int d0 = 0; d0 < 4; ++d0) { const int cb = (d0 * 16 + hi * 8) * 2;
;     const bf16x8 f = *reinterpret_cast<const bf16x8*>(Kr + KRSWZ(32 * H + r32, cb)); p = __builtin_amdgcn_mfma_f32_32x32x16_bf16(f, qr[8 + d0], p, 0, 0, 0); }
; }
.LBB0_521:
	ds_read_b128 v[70:73], v188 offset:32768
	v_mfma_f32_32x32x16_bf16 v[82:97], v[250:253], v[252:255], 0
	s_waitcnt lgkmcnt(3)
	v_mfma_f32_32x32x16_bf16 v[82:97], v[66:69], v[98:101], v[82:97]
	ds_read_b128 v[66:69], v191 offset:32768
	s_waitcnt lgkmcnt(3)
	v_mfma_f32_32x32x16_bf16 v[82:97], v[74:77], v[106:109], v[82:97]
	ds_read_b128 v[74:77], v193 offset:32768
	s_waitcnt lgkmcnt(3)
	v_mfma_f32_32x32x16_bf16 v[82:97], v[78:81], v[110:113], v[82:97]
	ds_read_b128 v[78:81], v194 offset:32768
	s_waitcnt lgkmcnt(3)
	v_mfma_f32_32x32x16_bf16 v[82:97], v[70:73], v[102:105], v[82:97]
	ds_read_b128 v[70:73], v192 offset:32768
	s_waitcnt lgkmcnt(3)
	v_mfma_f32_32x32x16_bf16 v[82:97], v[66:69], v[114:117], v[82:97]
	ds_read_b128 v[66:69], v157
	s_waitcnt lgkmcnt(3)
	v_mfma_f32_32x32x16_bf16 v[82:97], v[74:77], v[122:125], v[82:97]
	ds_read_b128 v[74:77], v159
	s_waitcnt lgkmcnt(3)
	v_mfma_f32_32x32x16_bf16 v[82:97], v[78:81], v[126:129], v[82:97]
	ds_read_b128 v[78:81], v160
	s_waitcnt lgkmcnt(3)
	v_mfma_f32_32x32x16_bf16 v[82:97], v[70:73], v[118:121], v[82:97]
	ds_read_b128 v[70:73], v158
	s_waitcnt lgkmcnt(3)
	v_mfma_f32_32x32x16_bf16 v[82:97], v[66:69], v[130:133], v[82:97]
	ds_read_b128 v[66:69], v187 offset:40960
	ds_read_b128 v[168:171], v188 offset:40960
	s_waitcnt lgkmcnt(4)
	v_mfma_f32_32x32x16_bf16 v[82:97], v[74:77], v[138:141], v[82:97]
	ds_read_b128 v[198:201], v189 offset:40960
	ds_read_b128 v[202:205], v190 offset:40960
	s_waitcnt lgkmcnt(5)
	v_mfma_f32_32x32x16_bf16 v[82:97], v[78:81], v[142:145], v[82:97]
	ds_read_b128 v[206:209], v191 offset:40960
	ds_read_b128 v[210:213], v192 offset:40960
	s_waitcnt lgkmcnt(6)
	v_mfma_f32_32x32x16_bf16 v[82:97], v[70:73], v[134:137], v[82:97]
	ds_read_b128 v[214:217], v193 offset:40960
	ds_read_b128 v[218:221], v194 offset:40960
	s_andn2_b64 vcc, exec, s[62:63]
	s_cbranch_vccnz .Ldma_b0_skip
	s_add_i32 m0, s84, 0x12000
	s_nop 0
	global_load_lds_dwordx4 v154, s[20:21]
	s_add_i32 m0, s81, 0x4000
	s_nop 0
	global_load_lds_dwordx4 v155, s[34:35]
	s_add_i32 m0, s81, 0x4400
	s_nop 0
	global_load_lds_dwordx4 v156, s[34:35]
	s_add_u32 s20, s20, 0x2000
	s_addc_u32 s21, s21, 0
	s_add_u32 s34, s34, 0x18000
	s_addc_u32 s35, s35, 0

; #define VWAIT(N, f) asm volatile("s_waitcnt lgkmcnt(" #N ")" : "+v"(f.l0), "+v"(f.h0), "+v"(f.l1), "+v"(f.h1) :: "memory")
; template <int H> __device__ __forceinline__ void qkt_half(f32x16& p, const char* Kn, const char* Kr, const bf16x8* qr, int r32, int hi) {
;   p = f32x16{};
; #pragma unroll
;   for (int d0 = 0; d0 < 8; ++d0) { const int cb = (d0 * 16 + hi * 8) * 2;
;     const bf16x8 f = *reinterpret_cast<const bf16x8*>(Kn + KSWZ(32 * H + r32, cb)); p = __builtin_amdgcn_mfma_f32_32x32x16_bf16(f, qr[d0], p, 0, 0, 0); }
; #pragma unroll
;   for (int d0 = 0; d0 < 4; ++d0) { const int cb = (d0 * 16 + hi * 8) * 2;
;     const bf16x8 f = *reinterpret_cast<const bf16x8*>(Kr + KRSWZ(32 * H + r32, cb)); p = __builtin_amdgcn_mfma_f32_32x32x16_bf16(f, qr[8 + d0], p, 0, 0, 0); }
; }
; template <int H, int D0> __device__ __forceinline__ VFrag pv_rd(int vb) {
;   VFrag f; f.l0 = tr_read<v_rd_off(D0, 2 * H, 0)>(vb); f.h0 = tr_read<v_rd_off(D0, 2 * H, 1)>(vb); f.l1 = tr_read<v_rd_off(D0, 2 * H + 1, 0)>(vb); f.h1 = tr_read<v_rd_off(D0, 2 * H + 1, 1)>(vb); return f;
; }
; __device__ __forceinline__ void pv_mma(f32x16& od, VFrag& f, bf16x8 paL, bf16x8 paH) {
;     ...
;   od = __builtin_amdgcn_mfma_f32_32x32x16_bf16(paL, PK(f.l0, f.h0), od, 0, 0, 0);
;   od = __builtin_amdgcn_mfma_f32_32x32x16_bf16(paH, PK(f.l1, f.h1), od, 0, 0, 0);
;     ...
; }
; template <int H> __device__ __forceinline__ void pv_half(f32x16* o, int vb, bf16x8 paL, bf16x8 paH) {
;   VFrag fa = pv_rd<H, 0>(vb), fb = pv_rd<H, 1>(vb);
;   VWAIT(4, fa); pv_mma(o[0], fa, paL, paH);
;   fa = pv_rd<H, 2>(vb);
;   VWAIT(4, fb); pv_mma(o[1], fb, paL, paH);
;   fb = pv_rd<H, 3>(vb);
;   VWAIT(4, fa); pv_mma(o[2], fa, paL, paH);
;   VWAIT(0, fb); pv_mma(o[3], fb, paL, paH);
; }
.LBB0_531:
	ds_read_b64_tr_b16 v[90:91], v175 offset:0x2000
	ds_read_b64_tr_b16 v[92:93], v175 offset:0x2800
	ds_read_b64_tr_b16 v[82:83], v175 offset:0x2200
	ds_read_b64_tr_b16 v[84:85], v175 offset:0x2a00
	ds_read_b64_tr_b16 v[202:203], v175 offset:0x2400
	ds_read_b64_tr_b16 v[204:205], v175 offset:0x2c00
	ds_read_b64_tr_b16 v[206:207], v175 offset:0x2600
	ds_read_b64_tr_b16 v[208:209], v175 offset:0x2e00
	ds_read_b64_tr_b16 v[94:95], v175 offset:0x3000
	ds_read_b64_tr_b16 v[96:97], v175 offset:0x3800
	ds_read_b64_tr_b16 v[86:87], v175 offset:0x3200
	ds_read_b64_tr_b16 v[88:89], v175 offset:0x3a00
	v_exp_f32_e32 v74, v74
	v_exp_f32_e32 v75, v75
	s_cmp_lt_u32 s87, s79
	s_cselect_b64 s[64:65], -1, 0
	s_cmp_ge_u32 s87, s79
	s_cselect_b64 s[62:63], -1, 0
	s_and_b64 vcc, exec, s[62:63]
	s_waitcnt lgkmcnt(10)
	v_mfma_f32_32x32x16_bf16 v[50:65], v[66:69], v[90:93], v[50:65]
	ds_read_b64_tr_b16 v[90:91], v175 offset:0x3400
	ds_read_b64_tr_b16 v[92:93], v175 offset:0x3c00
	v_exp_f32_e32 v76, v76
	v_exp_f32_e32 v77, v77
	v_add_f32_e32 v201, v74, v201
	v_add_f32_e32 v201, v75, v201
	s_waitcnt lgkmcnt(10)
	v_mfma_f32_32x32x16_bf16 v[34:49], v[66:69], v[82:85], v[34:49]
	ds_read_b64_tr_b16 v[82:83], v175 offset:0x3600
	ds_read_b64_tr_b16 v[84:85], v175 offset:0x3e00
	v_exp_f32_e32 v78, v78
	v_exp_f32_e32 v79, v79
	v_add_f32_e32 v201, v76, v201
	v_add_f32_e32 v201, v77, v201
	v_cvt_pk_bf16_f32 v70, v74, v75
	v_cvt_pk_bf16_f32 v71, v76, v77
	s_waitcnt lgkmcnt(10)
	v_mfma_f32_32x32x16_bf16 v[18:33], v[66:69], v[202:205], v[18:33]
	v_exp_f32_e32 v80, v80
	v_exp_f32_e32 v81, v81
	v_add_f32_e32 v201, v78, v201
	v_add_f32_e32 v201, v79, v201
	s_waitcnt lgkmcnt(8)
	v_mfma_f32_32x32x16_bf16 v[2:17], v[66:69], v[206:209], v[2:17]
	v_cvt_pk_bf16_f32 v72, v78, v79
	v_add_f32_e32 v201, v80, v201
	v_add_f32_e32 v201, v81, v201
	v_cvt_pk_bf16_f32 v73, v80, v81
	s_nop 1
	v_permlane32_swap_b32_e32 v70, v72
	v_permlane32_swap_b32_e32 v71, v73
	s_nop 1
	s_waitcnt vmcnt(0) lgkmcnt(0)
	v_mfma_f32_32x32x16_bf16 v[50:65], v[70:73], v[94:97], v[50:65]
	s_barrier
	ds_read_b128 v[66:69], v187 offset:49152
	ds_read_b128 v[74:77], v189 offset:49152
	ds_read_b128 v[78:81], v190 offset:49152
	v_mfma_f32_32x32x16_bf16 v[34:49], v[70:73], v[86:89], v[34:49]
	v_mfma_f32_32x32x16_bf16 v[18:33], v[70:73], v[90:93], v[18:33]
	v_mfma_f32_32x32x16_bf16 v[2:17], v[70:73], v[82:85], v[2:17]
	s_cbranch_vccnz .LBB0_533
	s_mov_b32 m0, s82
	s_nop 0
	global_load_lds_dwordx4 v152, s[18:19]
	s_mov_b32 m0, s83
	s_nop 0
	global_load_lds_dwordx4 v153, s[18:19]
	s_add_u32 s18, s18, 0x18000
	s_addc_u32 s19, s19, 0
.LBB0_533:
	ds_read_b128 v[70:73], v188 offset:49152
	v_mfma_f32_32x32x16_bf16 v[82:97], v[250:253], v[252:255], 0
	s_waitcnt lgkmcnt(3)
	v_mfma_f32_32x32x16_bf16 v[82:97], v[66:69], v[98:101], v[82:97]
	ds_read_b128 v[66:69], v191 offset:49152
	s_waitcnt lgkmcnt(3)
	v_mfma_f32_32x32x16_bf16 v[82:97], v[74:77], v[106:109], v[82:97]
	ds_read_b128 v[74:77], v193 offset:49152
	s_waitcnt lgkmcnt(3)
	v_mfma_f32_32x32x16_bf16 v[82:97], v[78:81], v[110:113], v[82:97]
	ds_read_b128 v[78:81], v194 offset:49152
	s_waitcnt lgkmcnt(3)
	v_mfma_f32_32x32x16_bf16 v[82:97], v[70:73], v[102:105], v[82:97]
	ds_read_b128 v[70:73], v192 offset:49152
	s_waitcnt lgkmcnt(3)
	v_mfma_f32_32x32x16_bf16 v[82:97], v[66:69], v[114:117], v[82:97]
	ds_read_b128 v[66:69], v157 offset:8192
	s_waitcnt lgkmcnt(3)
	v_mfma_f32_32x32x16_bf16 v[82:97], v[74:77], v[122:125], v[82:97]
	ds_read_b128 v[74:77], v159 offset:8192
	s_waitcnt lgkmcnt(3)
	v_mfma_f32_32x32x16_bf16 v[82:97], v[78:81], v[126:129], v[82:97]
	ds_read_b128 v[78:81], v160 offset:8192
	s_waitcnt lgkmcnt(3)
	v_mfma_f32_32x32x16_bf16 v[82:97], v[70:73], v[118:121], v[82:97]
	ds_read_b128 v[70:73], v158 offset:8192
	s_waitcnt lgkmcnt(3)
	v_mfma_f32_32x32x16_bf16 v[82:97], v[66:69], v[130:133], v[82:97]
	ds_read_b128 v[66:69], v187 offset:57344
	ds_read_b128 v[204:207], v188 offset:57344
	s_waitcnt lgkmcnt(4)
	v_mfma_f32_32x32x16_bf16 v[82:97], v[74:77], v[138:141], v[82:97]
	ds_read_b128 v[208:211], v189 offset:57344
	ds_read_b128 v[212:215], v190 offset:57344
	s_waitcnt lgkmcnt(5)
	v_mfma_f32_32x32x16_bf16 v[82:97], v[78:81], v[142:145], v[82:97]
	ds_read_b128 v[216:219], v191 offset:57344
	ds_read_b128 v[220:223], v192 offset:57344
	s_waitcnt lgkmcnt(6)
	v_mfma_f32_32x32x16_bf16 v[82:97], v[70:73], v[134:137], v[82:97]
	ds_read_b128 v[224:227], v193 offset:57344
	ds_read_b128 v[228:231], v194 offset:57344
	s_andn2_b64 vcc, exec, s[64:65]
	s_cbranch_vccnz .Ldma_b1_skip
	s_mov_b32 m0, s85
	s_nop 0
	global_load_lds_dwordx4 v154, s[20:21]
	s_mov_b32 m0, s81
	s_nop 0
	global_load_lds_dwordx4 v155, s[34:35]
	s_mov_b32 m0, s86
	s_nop 0
	global_load_lds_dwordx4 v156, s[34:35]
	s_add_u32 s20, s20, 0x2000
	s_addc_u32 s21, s21, 0
	s_add_u32 s34, s34, 0x18000
	s_addc_u32 s35, s35, 0

; __device__ __forceinline__ int crow(int r, int hi) { return (r & 3) + 8 * (r >> 2) + 4 * hi; }
; __device__ __forceinline__ unsigned cvtpk(float lo, float hi) { unsigned r; asm volatile("v_cvt_pk_bf16_f32 %0, %1, %2" : "=v"(r) : "v"(lo), "v"(hi)); return r; }
; __device__ __forceinline__ void attn_unit(const bf16_t* __restrict__ Qb, const bf16_t* __restrict__ KNh, const bf16_t* __restrict__ KRs, const bf16_t* __restrict__ Vh,
;                                           bf16_t* __restrict__ Ob, float* __restrict__ ssa, int seq, char* lds) {
;     ...
;   if (hi == 0) li_l[r32] = l_reg; asm volatile("s_waitcnt lgkmcnt(0)" ::: "memory");
;   int zo = 0; asm volatile("" : "+v"(zo));
;   bf16_t* Ow = Ob + (long)(wid * QBLK) * LDO; float* ssw = ssa + wid * QBLK;
; #pragma unroll
;   for (int r = 0; r < 16; ++r) { const int orow = crow(r, hi) + zo; const float rl = __builtin_amdgcn_rcpf(li_l[orow]); float s = 0.f;
; #pragma unroll
;     for (int d0 = 0; d0 < 4; ++d0) { const float v = o[d0][r] * rl; s += v * v; Ow[(long)orow * LDO + d0 * 32 + r32] = (bf16_t)(cvtpk(v, v) & 0xffffu); }
;     s += __shfl_xor(s, 1); s += __shfl_xor(s, 2); s += __shfl_xor(s, 4); s += __shfl_xor(s, 8); s += __shfl_xor(s, 16);
;     if (r32 == 0) atomicAdd(ssw + orow, s); }
.LBB0_542:
	s_waitcnt lgkmcnt(0)
	v_mov_b32_e32 v198, v197
	s_nop 1
	v_permlane32_swap_b32_e32 v197, v198
	v_add_f32_e32 v197, v197, v198
	s_and_saveexec_b64 s[62:63], s[0:1]
	ds_write_b32 v196, v197
	s_or_b64 exec, exec, s[62:63]
	v_mov_b32_e32 v0, 0
	s_waitcnt lgkmcnt(0)
	s_lshl_b64 s[62:63], s[58:59], 11
	v_add_u32_e32 v66, v0, v182
	v_lshl_add_u32 v72, v66, 2, s80
	ds_read_b32 v0, v72
	s_add_u32 s62, s24, s62
	s_addc_u32 s63, s25, s63
	s_add_u32 s60, s62, s60
	s_addc_u32 s61, s63, s61
	s_waitcnt lgkmcnt(0)
	v_rcp_f32_e32 v0, v0
	s_lshl_b64 s[58:59], s[58:59], 2
	s_add_u32 s62, s31, s58
	s_addc_u32 s63, s33, s59
	v_mul_f32_e32 v73, v34, v0
	v_mul_f32_e32 v75, v2, v0
	v_and_b32_e32 v2, 64, v195
	v_mul_f32_e32 v50, v50, v0
	v_mul_f32_e32 v34, v73, v73
	v_mul_f32_e32 v74, v18, v0
	v_xor_b32_e32 v0, 1, v195
	v_add_u32_e32 v76, 64, v2
	v_fmac_f32_e32 v34, v50, v50
	v_cmp_lt_i32_e32 vcc, v0, v76
	v_fmac_f32_e32 v34, v74, v74
	v_fmac_f32_e32 v34, v75, v75
	v_cndmask_b32_e32 v0, v195, v0, vcc
	v_lshlrev_b32_e32 v2, 2, v0
	ds_bpermute_b32 v0, v2, v34
	s_lshl_b64 s[58:59], s[16:17], 11
	s_add_u32 s58, s60, s58
	s_addc_u32 s59, s61, s59
	v_cvt_pk_bf16_f32 v50, v50, v50
	s_waitcnt lgkmcnt(0)
	v_add_f32_e32 v34, v34, v0
	v_xor_b32_e32 v0, 2, v195
	v_cmp_lt_i32_e32 vcc, v0, v76
	s_lshl_b64 s[60:61], s[16:17], 2
	s_add_u32 s60, s62, s60
	v_cndmask_b32_e32 v0, v195, v0, vcc
	v_lshlrev_b32_e32 v18, 2, v0
	ds_bpermute_b32 v67, v18, v34
	v_lshlrev_b32_e32 v0, 1, v148
	v_lshl_add_u64 v[68:69], s[58:59], 0, v[0:1]
	v_xor_b32_e32 v0, 4, v195
	v_cmp_lt_i32_e32 vcc, v0, v76
	s_waitcnt lgkmcnt(0)
	v_add_f32_e32 v34, v34, v67
	v_ashrrev_i32_e32 v67, 31, v66
	v_cndmask_b32_e32 v0, v195, v0, vcc
	v_lshlrev_b32_e32 v0, 2, v0
	ds_bpermute_b32 v77, v0, v34
	v_lshl_add_u64 v[68:69], v[68:69], 0, s[52:53]
	v_lshlrev_b64 v[70:71], 11, v[66:67]
	v_lshl_add_u64 v[70:71], v[68:69], 0, v[70:71]
	global_store_short v[70:71], v50, off
	s_waitcnt lgkmcnt(0)
	v_add_f32_e32 v77, v34, v77
	v_xor_b32_e32 v34, 8, v195
	v_cmp_lt_i32_e32 vcc, v34, v76
	v_cvt_pk_bf16_f32 v50, v73, v73
	global_store_short v[70:71], v50, off offset:64
	v_xor_b32_e32 v50, 16, v195
	v_cndmask_b32_e32 v34, v195, v34, vcc
	v_lshlrev_b32_e32 v34, 2, v34
	ds_bpermute_b32 v78, v34, v77
	v_cmp_lt_i32_e32 vcc, v50, v76
	v_cvt_pk_bf16_f32 v79, v74, v74
	s_addc_u32 s61, s63, s61
	global_store_short v[70:71], v79, off offset:128
	v_cndmask_b32_e32 v50, v195, v50, vcc
	s_waitcnt lgkmcnt(0)
	v_add_f32_e32 v73, v77, v78
	v_lshlrev_b32_e32 v50, 2, v50
	ds_bpermute_b32 v74, v50, v73
	v_cvt_pk_bf16_f32 v75, v75, v75
	global_store_short v[70:71], v75, off offset:192
	v_lshl_add_u64 v[70:71], v[66:67], 2, s[60:61]
	s_and_saveexec_b64 s[58:59], s[2:3]
	s_cbranch_execz .LBB0_546
	s_waitcnt lgkmcnt(0)
	v_add_f32_e32 v67, v73, v74
	global_atomic_add_f32 v[70:71], v67, off
